# v113 + ph_win/ph_down K-loops: LDS-DMA loads with SGPR-pair + zero-extended lane offset addresses use the saddr form (18 more 64-bit VALU adds dropped)
# baseline (speedup 1.0000x reference)
; #define PG8_STAGE(bufoff, gbase, voff) do { _Pragma("unroll") for (int _i = 0; _i < 2; ++_i) \
;         __builtin_amdgcn_global_load_lds((const unsigned*)((const char*)(gbase) + (voff)[_i]), (LAS unsigned*)(lds + (bufoff) + ldsw + _i * 8192), 16, 0, 0); } while (0)
; #define PG8_LDA(dst, b, h) do { _Pragma("unroll") for (int m = 0; m < 4; ++m) _Pragma("unroll") for (int k = 0; k < 2; ++k) dst[m][k] = *(const LAS bf16x8*)(lds + PG8_SA(b, h) + aoff + m * 2048 + k * 1024); } while (0)
; #define PG8_LDB(dst, b, h) do { _Pragma("unroll") for (int n = 0; n < 2; ++n) _Pragma("unroll") for (int k = 0; k < 2; ++k) dst[n][k] = *(const LAS bf16x8*)(lds + PG8_SB(b, h) + boff + n * 2048 + k * 1024); } while (0)
; #define PG8_MMA(ai, bj, At, Bt) do { __builtin_amdgcn_s_setprio(1); _Pragma("unroll") for (int m = 0; m < 4; ++m) _Pragma("unroll") for (int n = 0; n < 2; ++n) _Pragma("unroll") for (int k = 0; k < 2; ++k) \
;         acc[ai][bj][m][n] = __builtin_amdgcn_mfma_f32_16x16x32_bf16(Bt[n][k], At[m][k], acc[ai][bj][m][n], 0, 0, 0); __builtin_amdgcn_s_setprio(0); } while (0)
; #define PG8_WAIT_V(n) asm volatile("s_waitcnt vmcnt(" #n ")" ::: "memory")
; #define PG8_WAIT_L(n) asm volatile("s_waitcnt lgkmcnt(" #n ")" ::: "memory")
; #define PG8_BAR __builtin_amdgcn_s_barrier()
; #define PG8_SCHED __builtin_amdgcn_sched_barrier(0)
; template <class Epi>
; DI void gemm_phase(LAS unsigned char* lds, const Gemm g, const StaticOrder& S, const Epi& E) {
;     ...
;             PG8_LDB(B0, 0, 0); PG8_LDB(B1, 0, 1); PG8_SCHED; PG8_LDA(At, 0, 0); PG8_STAGE(PG8_SA(1, 1), a1 + hstep, voffA);
;             PG8_WAIT_V(8); PG8_WAIT_L(0); PG8_BAR; PG8_MMA(0, 0, At, B0); PG8_MMA(0, 1, At, B1); PG8_BAR; PG8_SCHED;
;             PG8_LDA(At, 0, 1); PG8_STAGE(PG8_SB(0, 0), b2, voffB); PG8_STAGE(PG8_SB(0, 1), b2 + hstep, voffB); PG8_STAGE(PG8_SA(0, 0), a2, voffA);
;             PG8_WAIT_V(8); PG8_WAIT_L(0); PG8_BAR; PG8_MMA(1, 0, At, B0); PG8_MMA(1, 1, At, B1); PG8_BAR; PG8_SCHED;
.Lsp_5:
	s_add_u32 s18, s62, 0xfffc0080
	s_addc_u32 s19, s63, -1
	s_add_i32 s55, 0, 0x10000
	s_cmp_eq_u32 s53, 12
	s_cselect_b32 s67, s7, s19
	s_cselect_b32 s66, s17, s18
	s_cselect_b32 s65, s22, s43
	s_cselect_b32 s64, s23, s42
	s_add_i32 s18, 0, 0x14000
	v_add_u32_e32 v118, s55, v195
	v_add_u32_e32 v158, s18, v195
	ds_read_b128 v[66:69], v118
	ds_read_b128 v[78:81], v118 offset:1024
	ds_read_b128 v[98:101], v118 offset:2048
	ds_read_b128 v[118:121], v118 offset:3072
	ds_read_b128 v[138:141], v158
	ds_read_b128 v[142:145], v158 offset:1024
	ds_read_b128 v[154:157], v158 offset:2048
	ds_read_b128 v[158:161], v158 offset:3072
	s_add_i32 m0, s37, 0xc000
	ds_read_b128 v[162:165], v246
	ds_read_b128 v[166:169], v246 offset:1024
	ds_read_b128 v[170:173], v246 offset:2048
	ds_read_b128 v[174:177], v246 offset:3072
	ds_read_b128 v[178:181], v246 offset:4096
	ds_read_b128 v[182:185], v246 offset:5120
	ds_read_b128 v[186:189], v246 offset:6144
	ds_read_b128 v[190:193], v246 offset:7168
	global_load_lds_dwordx4 v222, s[62:63]
	s_add_i32 m0, s37, 0xe000
	s_nop 0
	global_load_lds_dwordx4 v220, s[62:63]
	s_waitcnt vmcnt(8)
	s_waitcnt lgkmcnt(0)
	s_barrier
	s_waitcnt lgkmcnt(0)
	v_mfma_f32_16x16x32_bf16 v[150:153], v[66:69], v[162:165], 0
	v_mfma_f32_16x16x32_bf16 v[146:149], v[98:101], v[162:165], 0
	v_mfma_f32_16x16x32_bf16 v[126:129], v[66:69], v[170:173], 0
	v_mfma_f32_16x16x32_bf16 v[122:125], v[98:101], v[170:173], 0
	v_mfma_f32_16x16x32_bf16 v[106:109], v[66:69], v[178:181], 0
	v_mfma_f32_16x16x32_bf16 v[102:105], v[98:101], v[178:181], 0
	v_mfma_f32_16x16x32_bf16 v[86:89], v[66:69], v[186:189], 0
	v_mfma_f32_16x16x32_bf16 v[82:85], v[98:101], v[186:189], 0
	v_mfma_f32_16x16x32_bf16 v[150:153], v[78:81], v[166:169], v[150:153]
	v_mfma_f32_16x16x32_bf16 v[146:149], v[118:121], v[166:169], v[146:149]
	v_mfma_f32_16x16x32_bf16 v[126:129], v[78:81], v[174:177], v[126:129]
	v_mfma_f32_16x16x32_bf16 v[122:125], v[118:121], v[174:177], v[122:125]
	v_mfma_f32_16x16x32_bf16 v[106:109], v[78:81], v[182:185], v[106:109]
	v_mfma_f32_16x16x32_bf16 v[102:105], v[118:121], v[182:185], v[102:105]
	v_mfma_f32_16x16x32_bf16 v[86:89], v[78:81], v[190:193], v[86:89]
	v_mfma_f32_16x16x32_bf16 v[82:85], v[118:121], v[190:193], v[82:85]
	v_mfma_f32_16x16x32_bf16 v[134:137], v[138:141], v[162:165], 0
	v_mfma_f32_16x16x32_bf16 v[130:133], v[154:157], v[162:165], 0
	v_mfma_f32_16x16x32_bf16 v[114:117], v[138:141], v[170:173], 0
	v_mfma_f32_16x16x32_bf16 v[110:113], v[154:157], v[170:173], 0
	v_mfma_f32_16x16x32_bf16 v[94:97], v[138:141], v[178:181], 0
	v_mfma_f32_16x16x32_bf16 v[90:93], v[154:157], v[178:181], 0
	v_mfma_f32_16x16x32_bf16 v[74:77], v[138:141], v[186:189], 0
	v_mfma_f32_16x16x32_bf16 v[70:73], v[154:157], v[186:189], 0
	v_mfma_f32_16x16x32_bf16 v[134:137], v[142:145], v[166:169], v[134:137]
	v_mfma_f32_16x16x32_bf16 v[130:133], v[158:161], v[166:169], v[130:133]
	v_mfma_f32_16x16x32_bf16 v[114:117], v[142:145], v[174:177], v[114:117]
	v_mfma_f32_16x16x32_bf16 v[110:113], v[158:161], v[174:177], v[110:113]
	v_mfma_f32_16x16x32_bf16 v[94:97], v[142:145], v[182:185], v[94:97]
	v_mfma_f32_16x16x32_bf16 v[90:93], v[158:161], v[182:185], v[90:93]
	v_mfma_f32_16x16x32_bf16 v[74:77], v[142:145], v[190:193], v[74:77]
	v_mfma_f32_16x16x32_bf16 v[70:73], v[158:161], v[190:193], v[70:73]
	s_barrier
	s_add_i32 s19, s55, s36
	v_lshl_add_u64 v[200:201], s[64:65], 0, v[208:209]
	s_mov_b32 m0, s19
	ds_read_b128 v[162:165], v246 offset:16384
	ds_read_b128 v[166:169], v246 offset:17408
	ds_read_b128 v[170:173], v246 offset:18432
	ds_read_b128 v[174:177], v246 offset:19456
	ds_read_b128 v[178:181], v246 offset:20480
	ds_read_b128 v[182:185], v246 offset:21504
	ds_read_b128 v[186:189], v246 offset:22528
	ds_read_b128 v[190:193], v246 offset:23552
	global_load_lds_dwordx4 v[200:201], off
	s_add_i32 m0, s19, 0x2000
	s_add_u32 s94, s64, 0x40000
	v_lshl_add_u64 v[202:203], s[64:65], 0, v[212:213]
	s_addc_u32 s95, s65, 0
	s_add_i32 s18, s18, s36
	global_load_lds_dwordx4 v[202:203], off
	s_mov_b32 m0, s18
	v_lshl_add_u64 v[226:227], s[66:67], 0, v[210:211]
	global_load_lds_dwordx4 v208, s[94:95]
	s_add_i32 m0, s18, 0x2000
	s_nop 0
	global_load_lds_dwordx4 v212, s[94:95]
	v_lshl_add_u64 v[224:225], s[66:67], 0, v[206:207]
	s_mov_b32 m0, s37
	s_nop 0
	global_load_lds_dwordx4 v[224:225], off
	s_mov_b32 m0, s61
	s_nop 0
	global_load_lds_dwordx4 v[226:227], off
	s_waitcnt vmcnt(8)
	s_waitcnt lgkmcnt(0)
	s_barrier
	s_waitcnt lgkmcnt(0)
	v_mfma_f32_16x16x32_bf16 v[62:65], v[66:69], v[162:165], 0
	v_mfma_f32_16x16x32_bf16 v[58:61], v[98:101], v[162:165], 0
	v_mfma_f32_16x16x32_bf16 v[46:49], v[66:69], v[170:173], 0
	v_mfma_f32_16x16x32_bf16 v[42:45], v[98:101], v[170:173], 0
	v_mfma_f32_16x16x32_bf16 v[30:33], v[66:69], v[178:181], 0
	v_mfma_f32_16x16x32_bf16 v[26:29], v[98:101], v[178:181], 0
	v_mfma_f32_16x16x32_bf16 v[14:17], v[66:69], v[186:189], 0
	v_mfma_f32_16x16x32_bf16 v[10:13], v[98:101], v[186:189], 0
	v_mfma_f32_16x16x32_bf16 v[62:65], v[78:81], v[166:169], v[62:65]
	v_mfma_f32_16x16x32_bf16 v[58:61], v[118:121], v[166:169], v[58:61]
	v_mfma_f32_16x16x32_bf16 v[46:49], v[78:81], v[174:177], v[46:49]
	v_mfma_f32_16x16x32_bf16 v[42:45], v[118:121], v[174:177], v[42:45]
	v_mfma_f32_16x16x32_bf16 v[30:33], v[78:81], v[182:185], v[30:33]
	v_mfma_f32_16x16x32_bf16 v[26:29], v[118:121], v[182:185], v[26:29]
	v_mfma_f32_16x16x32_bf16 v[14:17], v[78:81], v[190:193], v[14:17]
	v_mfma_f32_16x16x32_bf16 v[10:13], v[118:121], v[190:193], v[10:13]
	v_mfma_f32_16x16x32_bf16 v[54:57], v[138:141], v[162:165], 0
	v_mfma_f32_16x16x32_bf16 v[50:53], v[154:157], v[162:165], 0
	v_mfma_f32_16x16x32_bf16 v[38:41], v[138:141], v[170:173], 0
	v_mfma_f32_16x16x32_bf16 v[34:37], v[154:157], v[170:173], 0
	v_mfma_f32_16x16x32_bf16 v[22:25], v[138:141], v[178:181], 0
	v_mfma_f32_16x16x32_bf16 v[18:21], v[154:157], v[178:181], 0
	v_mfma_f32_16x16x32_bf16 v[6:9], v[138:141], v[186:189], 0
	v_mfma_f32_16x16x32_bf16 v[2:5], v[154:157], v[186:189], 0
	v_mfma_f32_16x16x32_bf16 v[54:57], v[142:145], v[166:169], v[54:57]
	v_mfma_f32_16x16x32_bf16 v[50:53], v[158:161], v[166:169], v[50:53]
	v_mfma_f32_16x16x32_bf16 v[38:41], v[142:145], v[174:177], v[38:41]
	v_mfma_f32_16x16x32_bf16 v[34:37], v[158:161], v[174:177], v[34:37]
	v_mfma_f32_16x16x32_bf16 v[22:25], v[142:145], v[182:185], v[22:25]
	v_mfma_f32_16x16x32_bf16 v[18:21], v[158:161], v[182:185], v[18:21]
	v_mfma_f32_16x16x32_bf16 v[6:9], v[142:145], v[190:193], v[6:9]
	v_mfma_f32_16x16x32_bf16 v[2:5], v[158:161], v[190:193], v[2:5]
	s_barrier
	s_branch .Lp3_win
; #define PG8_STAGE(bufoff, gbase, voff) do { _Pragma("unroll") for (int _i = 0; _i < 2; ++_i) \
;         __builtin_amdgcn_global_load_lds((const unsigned*)((const char*)(gbase) + (voff)[_i]), (LAS unsigned*)(lds + (bufoff) + ldsw + _i * 8192), 16, 0, 0); } while (0)
; #define PG8_LDA(dst, b, h) do { _Pragma("unroll") for (int m = 0; m < 4; ++m) _Pragma("unroll") for (int k = 0; k < 2; ++k) dst[m][k] = *(const LAS bf16x8*)(lds + PG8_SA(b, h) + aoff + m * 2048 + k * 1024); } while (0)
; #define PG8_LDB(dst, b, h) do { _Pragma("unroll") for (int n = 0; n < 2; ++n) _Pragma("unroll") for (int k = 0; k < 2; ++k) dst[n][k] = *(const LAS bf16x8*)(lds + PG8_SB(b, h) + boff + n * 2048 + k * 1024); } while (0)
; #define PG8_MMA(ai, bj, At, Bt) do { __builtin_amdgcn_s_setprio(1); _Pragma("unroll") for (int m = 0; m < 4; ++m) _Pragma("unroll") for (int n = 0; n < 2; ++n) _Pragma("unroll") for (int k = 0; k < 2; ++k) \
;         acc[ai][bj][m][n] = __builtin_amdgcn_mfma_f32_16x16x32_bf16(Bt[n][k], At[m][k], acc[ai][bj][m][n], 0, 0, 0); __builtin_amdgcn_s_setprio(0); } while (0)
; #define PG8_WAIT_V(n) asm volatile("s_waitcnt vmcnt(" #n ")" ::: "memory")
; #define PG8_WAIT_L(n) asm volatile("s_waitcnt lgkmcnt(" #n ")" ::: "memory")
; #define PG8_BAR __builtin_amdgcn_s_barrier()
; #define PG8_SCHED __builtin_amdgcn_sched_barrier(0)
; template <class Epi>
; DI void gemm_phase(LAS unsigned char* lds, const Gemm g, const StaticOrder& S, const Epi& E) {
;     ...
;             PG8_LDB(B0, 0, 0); PG8_LDB(B1, 0, 1); PG8_SCHED; PG8_LDA(At, 0, 0); PG8_STAGE(PG8_SA(1, 1), a1 + hstep, voffA);
;             PG8_WAIT_V(8); PG8_WAIT_L(0); PG8_BAR; PG8_MMA(0, 0, At, B0); PG8_MMA(0, 1, At, B1); PG8_BAR; PG8_SCHED;
;             PG8_LDA(At, 0, 1); PG8_STAGE(PG8_SB(0, 0), b2, voffB); PG8_STAGE(PG8_SB(0, 1), b2 + hstep, voffB); PG8_STAGE(PG8_SA(0, 0), a2, voffA);
;             PG8_WAIT_V(8); PG8_WAIT_L(0); PG8_BAR; PG8_MMA(1, 0, At, B0); PG8_MMA(1, 1, At, B1); PG8_BAR; PG8_SCHED;
.LBB0_92:
	s_add_u32 s18, s62, 0xfffc0080
	s_addc_u32 s19, s63, -1
	s_add_i32 s55, 0, 0x10000
	s_cmp_eq_u32 s53, 12
	s_cselect_b32 s67, s7, s19
	s_cselect_b32 s66, s17, s18
	s_cselect_b32 s65, s22, s43
	s_cselect_b32 s64, s23, s42
	s_add_i32 s18, 0, 0x14000
	v_add_u32_e32 v118, s55, v195
	v_add_u32_e32 v158, s18, v195
	ds_read_b128 v[66:69], v118
	ds_read_b128 v[78:81], v118 offset:1024
	ds_read_b128 v[98:101], v118 offset:2048
	ds_read_b128 v[118:121], v118 offset:3072
	ds_read_b128 v[138:141], v158
	ds_read_b128 v[142:145], v158 offset:1024
	ds_read_b128 v[154:157], v158 offset:2048
	ds_read_b128 v[158:161], v158 offset:3072
	s_add_i32 m0, s37, 0xc000
	ds_read_b128 v[162:165], v246
	ds_read_b128 v[166:169], v246 offset:1024
	ds_read_b128 v[170:173], v246 offset:2048
	ds_read_b128 v[174:177], v246 offset:3072
	ds_read_b128 v[178:181], v246 offset:4096
	ds_read_b128 v[182:185], v246 offset:5120
	ds_read_b128 v[186:189], v246 offset:6144
	ds_read_b128 v[190:193], v246 offset:7168
	global_load_lds_dwordx4 v222, s[62:63]
	s_add_i32 m0, s37, 0xe000
	s_nop 0
	global_load_lds_dwordx4 v220, s[62:63]
	s_waitcnt vmcnt(8)
	s_waitcnt lgkmcnt(0)
	s_barrier
	s_waitcnt lgkmcnt(0)
	v_mfma_f32_16x16x32_bf16 v[150:153], v[66:69], v[162:165], v[150:153]
	v_mfma_f32_16x16x32_bf16 v[146:149], v[98:101], v[162:165], v[146:149]
	v_mfma_f32_16x16x32_bf16 v[126:129], v[66:69], v[170:173], v[126:129]
	v_mfma_f32_16x16x32_bf16 v[122:125], v[98:101], v[170:173], v[122:125]
	v_mfma_f32_16x16x32_bf16 v[106:109], v[66:69], v[178:181], v[106:109]
	v_mfma_f32_16x16x32_bf16 v[102:105], v[98:101], v[178:181], v[102:105]
	v_mfma_f32_16x16x32_bf16 v[86:89], v[66:69], v[186:189], v[86:89]
	v_mfma_f32_16x16x32_bf16 v[82:85], v[98:101], v[186:189], v[82:85]
	v_mfma_f32_16x16x32_bf16 v[150:153], v[78:81], v[166:169], v[150:153]
	v_mfma_f32_16x16x32_bf16 v[146:149], v[118:121], v[166:169], v[146:149]
	v_mfma_f32_16x16x32_bf16 v[126:129], v[78:81], v[174:177], v[126:129]
	v_mfma_f32_16x16x32_bf16 v[122:125], v[118:121], v[174:177], v[122:125]
	v_mfma_f32_16x16x32_bf16 v[106:109], v[78:81], v[182:185], v[106:109]
	v_mfma_f32_16x16x32_bf16 v[102:105], v[118:121], v[182:185], v[102:105]
	v_mfma_f32_16x16x32_bf16 v[86:89], v[78:81], v[190:193], v[86:89]
	v_mfma_f32_16x16x32_bf16 v[82:85], v[118:121], v[190:193], v[82:85]
	v_mfma_f32_16x16x32_bf16 v[134:137], v[138:141], v[162:165], v[134:137]
	v_mfma_f32_16x16x32_bf16 v[130:133], v[154:157], v[162:165], v[130:133]
	v_mfma_f32_16x16x32_bf16 v[114:117], v[138:141], v[170:173], v[114:117]
	v_mfma_f32_16x16x32_bf16 v[110:113], v[154:157], v[170:173], v[110:113]
	v_mfma_f32_16x16x32_bf16 v[94:97], v[138:141], v[178:181], v[94:97]
	v_mfma_f32_16x16x32_bf16 v[90:93], v[154:157], v[178:181], v[90:93]
	v_mfma_f32_16x16x32_bf16 v[74:77], v[138:141], v[186:189], v[74:77]
	v_mfma_f32_16x16x32_bf16 v[70:73], v[154:157], v[186:189], v[70:73]
	v_mfma_f32_16x16x32_bf16 v[134:137], v[142:145], v[166:169], v[134:137]
	v_mfma_f32_16x16x32_bf16 v[130:133], v[158:161], v[166:169], v[130:133]
	v_mfma_f32_16x16x32_bf16 v[114:117], v[142:145], v[174:177], v[114:117]
	v_mfma_f32_16x16x32_bf16 v[110:113], v[158:161], v[174:177], v[110:113]
	v_mfma_f32_16x16x32_bf16 v[94:97], v[142:145], v[182:185], v[94:97]
	v_mfma_f32_16x16x32_bf16 v[90:93], v[158:161], v[182:185], v[90:93]
	v_mfma_f32_16x16x32_bf16 v[74:77], v[142:145], v[190:193], v[74:77]
	v_mfma_f32_16x16x32_bf16 v[70:73], v[158:161], v[190:193], v[70:73]
	s_barrier
	s_add_i32 s19, s55, s36
	v_lshl_add_u64 v[200:201], s[64:65], 0, v[208:209]
	s_mov_b32 m0, s19
	ds_read_b128 v[162:165], v246 offset:16384
	ds_read_b128 v[166:169], v246 offset:17408
	ds_read_b128 v[170:173], v246 offset:18432
	ds_read_b128 v[174:177], v246 offset:19456
	ds_read_b128 v[178:181], v246 offset:20480
	ds_read_b128 v[182:185], v246 offset:21504
	ds_read_b128 v[186:189], v246 offset:22528
	ds_read_b128 v[190:193], v246 offset:23552
	global_load_lds_dwordx4 v[200:201], off
	s_add_i32 m0, s19, 0x2000
	s_add_u32 s94, s64, 0x40000
	v_lshl_add_u64 v[202:203], s[64:65], 0, v[212:213]
	s_addc_u32 s95, s65, 0
	s_add_i32 s18, s18, s36
	global_load_lds_dwordx4 v[202:203], off
	s_mov_b32 m0, s18
	v_lshl_add_u64 v[226:227], s[66:67], 0, v[210:211]
	global_load_lds_dwordx4 v208, s[94:95]
	s_add_i32 m0, s18, 0x2000
	s_nop 0
	global_load_lds_dwordx4 v212, s[94:95]
	v_lshl_add_u64 v[224:225], s[66:67], 0, v[206:207]
	s_mov_b32 m0, s37
	s_nop 0
	global_load_lds_dwordx4 v[224:225], off
	s_mov_b32 m0, s61
	s_nop 0
	global_load_lds_dwordx4 v[226:227], off
	s_waitcnt vmcnt(8)
	s_waitcnt lgkmcnt(0)
	s_barrier
	s_waitcnt lgkmcnt(0)
	v_mfma_f32_16x16x32_bf16 v[62:65], v[66:69], v[162:165], v[62:65]
	v_mfma_f32_16x16x32_bf16 v[58:61], v[98:101], v[162:165], v[58:61]
	v_mfma_f32_16x16x32_bf16 v[46:49], v[66:69], v[170:173], v[46:49]
	v_mfma_f32_16x16x32_bf16 v[42:45], v[98:101], v[170:173], v[42:45]
	v_mfma_f32_16x16x32_bf16 v[30:33], v[66:69], v[178:181], v[30:33]
	v_mfma_f32_16x16x32_bf16 v[26:29], v[98:101], v[178:181], v[26:29]
	v_mfma_f32_16x16x32_bf16 v[14:17], v[66:69], v[186:189], v[14:17]
	v_mfma_f32_16x16x32_bf16 v[10:13], v[98:101], v[186:189], v[10:13]
	v_mfma_f32_16x16x32_bf16 v[62:65], v[78:81], v[166:169], v[62:65]
	v_mfma_f32_16x16x32_bf16 v[58:61], v[118:121], v[166:169], v[58:61]
	v_mfma_f32_16x16x32_bf16 v[46:49], v[78:81], v[174:177], v[46:49]
	v_mfma_f32_16x16x32_bf16 v[42:45], v[118:121], v[174:177], v[42:45]
	v_mfma_f32_16x16x32_bf16 v[30:33], v[78:81], v[182:185], v[30:33]
	v_mfma_f32_16x16x32_bf16 v[26:29], v[118:121], v[182:185], v[26:29]
	v_mfma_f32_16x16x32_bf16 v[14:17], v[78:81], v[190:193], v[14:17]
	v_mfma_f32_16x16x32_bf16 v[10:13], v[118:121], v[190:193], v[10:13]
	v_mfma_f32_16x16x32_bf16 v[54:57], v[138:141], v[162:165], v[54:57]
	v_mfma_f32_16x16x32_bf16 v[50:53], v[154:157], v[162:165], v[50:53]
	v_mfma_f32_16x16x32_bf16 v[38:41], v[138:141], v[170:173], v[38:41]
	v_mfma_f32_16x16x32_bf16 v[34:37], v[154:157], v[170:173], v[34:37]
	v_mfma_f32_16x16x32_bf16 v[22:25], v[138:141], v[178:181], v[22:25]
	v_mfma_f32_16x16x32_bf16 v[18:21], v[154:157], v[178:181], v[18:21]
	v_mfma_f32_16x16x32_bf16 v[6:9], v[138:141], v[186:189], v[6:9]
	v_mfma_f32_16x16x32_bf16 v[2:5], v[154:157], v[186:189], v[2:5]
	v_mfma_f32_16x16x32_bf16 v[54:57], v[142:145], v[166:169], v[54:57]
	v_mfma_f32_16x16x32_bf16 v[50:53], v[158:161], v[166:169], v[50:53]
	v_mfma_f32_16x16x32_bf16 v[38:41], v[142:145], v[174:177], v[38:41]
	v_mfma_f32_16x16x32_bf16 v[34:37], v[158:161], v[174:177], v[34:37]
	v_mfma_f32_16x16x32_bf16 v[22:25], v[142:145], v[182:185], v[22:25]
	v_mfma_f32_16x16x32_bf16 v[18:21], v[158:161], v[182:185], v[18:21]
	v_mfma_f32_16x16x32_bf16 v[6:9], v[142:145], v[190:193], v[6:9]
	v_mfma_f32_16x16x32_bf16 v[2:5], v[158:161], v[190:193], v[2:5]
	s_barrier
; #define PG8_STAGE(bufoff, gbase, voff) do { _Pragma("unroll") for (int _i = 0; _i < 2; ++_i) \
;         __builtin_amdgcn_global_load_lds((const unsigned*)((const char*)(gbase) + (voff)[_i]), (LAS unsigned*)(lds + (bufoff) + ldsw + _i * 8192), 16, 0, 0); } while (0)
; #define PG8_LDA(dst, b, h) do { _Pragma("unroll") for (int m = 0; m < 4; ++m) _Pragma("unroll") for (int k = 0; k < 2; ++k) dst[m][k] = *(const LAS bf16x8*)(lds + PG8_SA(b, h) + aoff + m * 2048 + k * 1024); } while (0)
; #define PG8_LDB(dst, b, h) do { _Pragma("unroll") for (int n = 0; n < 2; ++n) _Pragma("unroll") for (int k = 0; k < 2; ++k) dst[n][k] = *(const LAS bf16x8*)(lds + PG8_SB(b, h) + boff + n * 2048 + k * 1024); } while (0)
; #define PG8_MMA(ai, bj, At, Bt) do { __builtin_amdgcn_s_setprio(1); _Pragma("unroll") for (int m = 0; m < 4; ++m) _Pragma("unroll") for (int n = 0; n < 2; ++n) _Pragma("unroll") for (int k = 0; k < 2; ++k) \
;         acc[ai][bj][m][n] = __builtin_amdgcn_mfma_f32_16x16x32_bf16(Bt[n][k], At[m][k], acc[ai][bj][m][n], 0, 0, 0); __builtin_amdgcn_s_setprio(0); } while (0)
; #define PG8_WAIT_V(n) asm volatile("s_waitcnt vmcnt(" #n ")" ::: "memory")
; #define PG8_WAIT_L(n) asm volatile("s_waitcnt lgkmcnt(" #n ")" ::: "memory")
; #define PG8_BAR __builtin_amdgcn_s_barrier()
; #define PG8_SCHED __builtin_amdgcn_sched_barrier(0)
; template <class Epi>
; DI void gemm_phase(LAS unsigned char* lds, const Gemm g, const StaticOrder& S, const Epi& E) {
;     ...
;             PG8_LDB(B0, 1, 0); PG8_LDB(B1, 1, 1); PG8_SCHED; PG8_LDA(At, 1, 0); PG8_STAGE(PG8_SA(0, 1), a2 + hstep, voffA);
;             PG8_WAIT_V(8); PG8_WAIT_L(0); PG8_BAR; PG8_MMA(0, 0, At, B0); PG8_MMA(0, 1, At, B1); PG8_BAR; PG8_SCHED;
;             PG8_LDA(At, 1, 1); PG8_STAGE(PG8_SB(1, 0), b3, voffB); PG8_STAGE(PG8_SB(1, 1), b3 + hstep, voffB); PG8_STAGE(PG8_SA(1, 0), a3, voffA);
;             PG8_WAIT_V(8); PG8_WAIT_L(0); PG8_BAR; PG8_MMA(1, 0, At, B0); PG8_MMA(1, 1, At, B1); PG8_BAR; PG8_SCHED;
;         }
.Lp3_win:
	s_add_i32 s18, 0, 0x18000
	s_add_i32 s19, 0, 0x1c000
	v_add_u32_e32 v118, s18, v195
	v_add_u32_e32 v158, s19, v195
	ds_read_b128 v[66:69], v118
	ds_read_b128 v[78:81], v118 offset:1024
	ds_read_b128 v[98:101], v118 offset:2048
	ds_read_b128 v[118:121], v118 offset:3072
	ds_read_b128 v[138:141], v158
	ds_read_b128 v[142:145], v158 offset:1024
	ds_read_b128 v[154:157], v158 offset:2048
	ds_read_b128 v[158:161], v158 offset:3072
	s_add_u32 s66, s66, 0x40000
	s_addc_u32 s67, s67, 0
	s_mov_b32 m0, s68
	ds_read_b128 v[162:165], v246 offset:32768
	ds_read_b128 v[166:169], v246 offset:33792
	ds_read_b128 v[170:173], v246 offset:34816
	ds_read_b128 v[174:177], v246 offset:35840
	ds_read_b128 v[178:181], v246 offset:36864
	ds_read_b128 v[182:185], v246 offset:37888
	ds_read_b128 v[186:189], v246 offset:38912
	ds_read_b128 v[190:193], v246 offset:39936
	global_load_lds_dwordx4 v206, s[66:67]
	v_lshl_add_u64 v[228:229], s[66:67], 0, v[210:211]
	s_mov_b32 m0, s69
	s_nop 0
	global_load_lds_dwordx4 v[228:229], off
	s_waitcnt vmcnt(8)
	s_waitcnt lgkmcnt(0)
	s_barrier
	s_waitcnt lgkmcnt(0)
	v_mfma_f32_16x16x32_bf16 v[150:153], v[66:69], v[162:165], v[150:153]
	v_mfma_f32_16x16x32_bf16 v[146:149], v[98:101], v[162:165], v[146:149]
	v_mfma_f32_16x16x32_bf16 v[126:129], v[66:69], v[170:173], v[126:129]
	v_mfma_f32_16x16x32_bf16 v[122:125], v[98:101], v[170:173], v[122:125]
	v_mfma_f32_16x16x32_bf16 v[106:109], v[66:69], v[178:181], v[106:109]
	v_mfma_f32_16x16x32_bf16 v[102:105], v[98:101], v[178:181], v[102:105]
	v_mfma_f32_16x16x32_bf16 v[86:89], v[66:69], v[186:189], v[86:89]
	v_mfma_f32_16x16x32_bf16 v[82:85], v[98:101], v[186:189], v[82:85]
	v_mfma_f32_16x16x32_bf16 v[150:153], v[78:81], v[166:169], v[150:153]
	v_mfma_f32_16x16x32_bf16 v[146:149], v[118:121], v[166:169], v[146:149]
	v_mfma_f32_16x16x32_bf16 v[126:129], v[78:81], v[174:177], v[126:129]
	v_mfma_f32_16x16x32_bf16 v[122:125], v[118:121], v[174:177], v[122:125]
	v_mfma_f32_16x16x32_bf16 v[106:109], v[78:81], v[182:185], v[106:109]
	v_mfma_f32_16x16x32_bf16 v[102:105], v[118:121], v[182:185], v[102:105]
	v_mfma_f32_16x16x32_bf16 v[86:89], v[78:81], v[190:193], v[86:89]
	v_mfma_f32_16x16x32_bf16 v[82:85], v[118:121], v[190:193], v[82:85]
	v_mfma_f32_16x16x32_bf16 v[134:137], v[138:141], v[162:165], v[134:137]
	v_mfma_f32_16x16x32_bf16 v[130:133], v[154:157], v[162:165], v[130:133]
	v_mfma_f32_16x16x32_bf16 v[114:117], v[138:141], v[170:173], v[114:117]
	v_mfma_f32_16x16x32_bf16 v[110:113], v[154:157], v[170:173], v[110:113]
	v_mfma_f32_16x16x32_bf16 v[94:97], v[138:141], v[178:181], v[94:97]
	v_mfma_f32_16x16x32_bf16 v[90:93], v[154:157], v[178:181], v[90:93]
	v_mfma_f32_16x16x32_bf16 v[74:77], v[138:141], v[186:189], v[74:77]
	v_mfma_f32_16x16x32_bf16 v[70:73], v[154:157], v[186:189], v[70:73]
	v_mfma_f32_16x16x32_bf16 v[134:137], v[142:145], v[166:169], v[134:137]
	v_mfma_f32_16x16x32_bf16 v[130:133], v[158:161], v[166:169], v[130:133]
	v_mfma_f32_16x16x32_bf16 v[114:117], v[142:145], v[174:177], v[114:117]
	v_mfma_f32_16x16x32_bf16 v[110:113], v[158:161], v[174:177], v[110:113]
	v_mfma_f32_16x16x32_bf16 v[94:97], v[142:145], v[182:185], v[94:97]
	v_mfma_f32_16x16x32_bf16 v[90:93], v[158:161], v[182:185], v[90:93]
	v_mfma_f32_16x16x32_bf16 v[74:77], v[142:145], v[190:193], v[74:77]
	v_mfma_f32_16x16x32_bf16 v[70:73], v[158:161], v[190:193], v[70:73]
	s_barrier
	s_add_i32 s18, s18, s36
	v_lshl_add_u64 v[200:201], v[200:201], 0, s[20:21]
	s_mov_b32 m0, s18
	ds_read_b128 v[162:165], v246 offset:49152
	ds_read_b128 v[166:169], v246 offset:50176
	ds_read_b128 v[170:173], v246 offset:51200
	ds_read_b128 v[174:177], v246 offset:52224
	ds_read_b128 v[178:181], v246 offset:53248
	ds_read_b128 v[182:185], v246 offset:54272
	ds_read_b128 v[186:189], v246 offset:55296
	ds_read_b128 v[190:193], v246 offset:56320
	global_load_lds_dwordx4 v[200:201], off
	s_add_i32 m0, s18, 0x2000
	s_add_u32 s64, s64, 0x40080
	v_lshl_add_u64 v[200:201], v[202:203], 0, s[20:21]
	s_addc_u32 s65, s65, 0
	s_add_i32 s18, s19, s36
	global_load_lds_dwordx4 v[200:201], off
	s_mov_b32 m0, s18
	s_nop 0
	global_load_lds_dwordx4 v208, s[64:65]
	s_add_i32 m0, s18, 0x2000
	s_nop 0
	global_load_lds_dwordx4 v212, s[64:65]
	v_lshl_add_u64 v[200:201], v[224:225], 0, s[20:21]
	s_mov_b32 m0, s70
	s_nop 0
	global_load_lds_dwordx4 v[200:201], off
	v_lshl_add_u64 v[200:201], v[226:227], 0, s[20:21]
	s_mov_b32 m0, s71
	s_nop 0
	global_load_lds_dwordx4 v[200:201], off
	s_waitcnt vmcnt(8)
	s_waitcnt lgkmcnt(0)
	s_barrier
	s_waitcnt lgkmcnt(0)
	v_mfma_f32_16x16x32_bf16 v[62:65], v[66:69], v[162:165], v[62:65]
	v_mfma_f32_16x16x32_bf16 v[58:61], v[98:101], v[162:165], v[58:61]
	v_mfma_f32_16x16x32_bf16 v[46:49], v[66:69], v[170:173], v[46:49]
	v_mfma_f32_16x16x32_bf16 v[42:45], v[98:101], v[170:173], v[42:45]
	v_mfma_f32_16x16x32_bf16 v[30:33], v[66:69], v[178:181], v[30:33]
	v_mfma_f32_16x16x32_bf16 v[26:29], v[98:101], v[178:181], v[26:29]
	v_mfma_f32_16x16x32_bf16 v[14:17], v[66:69], v[186:189], v[14:17]
	v_mfma_f32_16x16x32_bf16 v[10:13], v[98:101], v[186:189], v[10:13]
	v_mfma_f32_16x16x32_bf16 v[62:65], v[78:81], v[166:169], v[62:65]
	v_mfma_f32_16x16x32_bf16 v[58:61], v[118:121], v[166:169], v[58:61]
	v_mfma_f32_16x16x32_bf16 v[46:49], v[78:81], v[174:177], v[46:49]
	v_mfma_f32_16x16x32_bf16 v[42:45], v[118:121], v[174:177], v[42:45]
	v_mfma_f32_16x16x32_bf16 v[30:33], v[78:81], v[182:185], v[30:33]
	v_mfma_f32_16x16x32_bf16 v[26:29], v[118:121], v[182:185], v[26:29]
	v_mfma_f32_16x16x32_bf16 v[14:17], v[78:81], v[190:193], v[14:17]
	v_mfma_f32_16x16x32_bf16 v[10:13], v[118:121], v[190:193], v[10:13]
	v_mfma_f32_16x16x32_bf16 v[54:57], v[138:141], v[162:165], v[54:57]
	v_mfma_f32_16x16x32_bf16 v[50:53], v[154:157], v[162:165], v[50:53]
	v_mfma_f32_16x16x32_bf16 v[38:41], v[138:141], v[170:173], v[38:41]
	v_mfma_f32_16x16x32_bf16 v[34:37], v[154:157], v[170:173], v[34:37]
	v_mfma_f32_16x16x32_bf16 v[22:25], v[138:141], v[178:181], v[22:25]
	v_mfma_f32_16x16x32_bf16 v[18:21], v[154:157], v[178:181], v[18:21]
	v_mfma_f32_16x16x32_bf16 v[6:9], v[138:141], v[186:189], v[6:9]
	v_mfma_f32_16x16x32_bf16 v[2:5], v[154:157], v[186:189], v[2:5]
	v_mfma_f32_16x16x32_bf16 v[54:57], v[142:145], v[166:169], v[54:57]
	v_mfma_f32_16x16x32_bf16 v[50:53], v[158:161], v[166:169], v[50:53]
	v_mfma_f32_16x16x32_bf16 v[38:41], v[142:145], v[174:177], v[38:41]
	v_mfma_f32_16x16x32_bf16 v[34:37], v[158:161], v[174:177], v[34:37]
	v_mfma_f32_16x16x32_bf16 v[22:25], v[142:145], v[182:185], v[22:25]
	v_mfma_f32_16x16x32_bf16 v[18:21], v[158:161], v[182:185], v[18:21]
	v_mfma_f32_16x16x32_bf16 v[6:9], v[142:145], v[190:193], v[6:9]
	v_mfma_f32_16x16x32_bf16 v[2:5], v[158:161], v[190:193], v[2:5]
	s_barrier
	s_add_i32 s53, s53, 2
	s_add_u32 s42, s42, 0x100
	s_addc_u32 s43, s43, 0
	s_add_u32 s62, s62, 0x100
	s_addc_u32 s63, s63, 0
	s_cmp_gt_u32 s53, 13
	s_cbranch_scc0 .LBB0_92
	s_setprio 0
	s_and_b64 vcc, exec, s[50:51]
	s_cbranch_vccz .LBB0_95
	s_barrier

; #define PG8_STAGE(bufoff, gbase, voff) do { _Pragma("unroll") for (int _i = 0; _i < 2; ++_i) \
;         __builtin_amdgcn_global_load_lds((const unsigned*)((const char*)(gbase) + (voff)[_i]), (LAS unsigned*)(lds + (bufoff) + ldsw + _i * 8192), 16, 0, 0); } while (0)
; #define PG8_LDA(dst, b, h) do { _Pragma("unroll") for (int m = 0; m < 4; ++m) _Pragma("unroll") for (int k = 0; k < 2; ++k) dst[m][k] = *(const LAS bf16x8*)(lds + PG8_SA(b, h) + aoff + m * 2048 + k * 1024); } while (0)
; #define PG8_LDB(dst, b, h) do { _Pragma("unroll") for (int n = 0; n < 2; ++n) _Pragma("unroll") for (int k = 0; k < 2; ++k) dst[n][k] = *(const LAS bf16x8*)(lds + PG8_SB(b, h) + boff + n * 2048 + k * 1024); } while (0)
; #define PG8_MMA(ai, bj, At, Bt) do { __builtin_amdgcn_s_setprio(1); _Pragma("unroll") for (int m = 0; m < 4; ++m) _Pragma("unroll") for (int n = 0; n < 2; ++n) _Pragma("unroll") for (int k = 0; k < 2; ++k) \
;         acc[ai][bj][m][n] = __builtin_amdgcn_mfma_f32_16x16x32_bf16(Bt[n][k], At[m][k], acc[ai][bj][m][n], 0, 0, 0); __builtin_amdgcn_s_setprio(0); } while (0)
; #define PG8_WAIT_V(n) asm volatile("s_waitcnt vmcnt(" #n ")" ::: "memory")
; #define PG8_WAIT_L(n) asm volatile("s_waitcnt lgkmcnt(" #n ")" ::: "memory")
; #define PG8_BAR __builtin_amdgcn_s_barrier()
; #define PG8_SCHED __builtin_amdgcn_sched_barrier(0)
; template <class Epi>
; DI void gemm_phase(LAS unsigned char* lds, const Gemm g, const StaticOrder& S, const Epi& E) {
;     ...
;             const bool last = (t == nt - 2);
;             const char* a1 = cA + (size_t)(t + 1) * kstep;
;             const char* a2 = last ? nA : cA + (size_t)(t + 2) * kstep; const char* b2 = last ? nB : cB + (size_t)(t + 2) * kstep;
;             const char* a3 = a2 + kstep; const char* b3 = b2 + kstep;
;             PG8_LDB(B0, 0, 0); PG8_LDB(B1, 0, 1); PG8_SCHED; PG8_LDA(At, 0, 0); PG8_STAGE(PG8_SA(1, 1), a1 + hstep, voffA);
;             PG8_WAIT_V(8); PG8_WAIT_L(0); PG8_BAR; PG8_MMA(0, 0, At, B0); PG8_MMA(0, 1, At, B1); PG8_BAR; PG8_SCHED;
;             PG8_LDA(At, 0, 1); PG8_STAGE(PG8_SB(0, 0), b2, voffB); PG8_STAGE(PG8_SB(0, 1), b2 + hstep, voffB); PG8_STAGE(PG8_SA(0, 0), a2, voffA);
;             PG8_WAIT_V(8); PG8_WAIT_L(0); PG8_BAR; PG8_MMA(1, 0, At, B0); PG8_MMA(1, 1, At, B1); PG8_BAR; PG8_SCHED;
.Lsp_0:
	s_add_u32 s60, s58, 0x100
	s_addc_u32 s61, s59, 0
	s_add_i32 s18, 0, 0x10000
	s_cmp_eq_u32 s93, 40
	s_cselect_b32 s65, s9, s61
	s_cselect_b32 s64, s8, s60
	s_cselect_b32 s63, s57, s91
	s_cselect_b32 s62, s56, s73
	s_add_i32 s81, 0, 0x14000
	v_add_u32_e32 v126, s18, v195
	v_add_u32_e32 v154, s81, v195
	ds_read_b128 v[114:117], v126
	ds_read_b128 v[118:121], v126 offset:1024
	ds_read_b128 v[122:125], v126 offset:2048
	ds_read_b128 v[126:129], v126 offset:3072
	ds_read_b128 v[134:137], v154
	ds_read_b128 v[138:141], v154 offset:1024
	ds_read_b128 v[146:149], v154 offset:2048
	ds_read_b128 v[154:157], v154 offset:3072
	v_lshl_add_u64 v[204:205], s[58:59], 0, v[184:185]
	s_add_i32 m0, s66, 0xc000
	ds_read_b128 v[162:165], v217
	ds_read_b128 v[166:169], v217 offset:1024
	ds_read_b128 v[170:173], v217 offset:2048
	ds_read_b128 v[174:177], v217 offset:3072
	ds_read_b128 v[186:189], v217 offset:4096
	ds_read_b128 v[190:193], v217 offset:5120
	ds_read_b128 v[200:203], v217 offset:6144
	ds_read_b128 v[206:209], v217 offset:7168
	global_load_lds_dwordx4 v[204:205], off
	v_lshl_add_u64 v[204:205], s[58:59], 0, v[182:183]
	s_add_i32 m0, s66, 0xe000
	s_nop 0
	global_load_lds_dwordx4 v[204:205], off
	s_waitcnt vmcnt(8)
	s_waitcnt lgkmcnt(0)
	s_barrier
	s_waitcnt lgkmcnt(0)
	v_mfma_f32_16x16x32_bf16 v[158:161], v[114:117], v[162:165], 0
	v_mfma_f32_16x16x32_bf16 v[150:153], v[122:125], v[162:165], 0
	v_mfma_f32_16x16x32_bf16 v[110:113], v[114:117], v[170:173], 0
	v_mfma_f32_16x16x32_bf16 v[106:109], v[122:125], v[170:173], 0
	v_mfma_f32_16x16x32_bf16 v[94:97], v[114:117], v[186:189], 0
	v_mfma_f32_16x16x32_bf16 v[90:93], v[122:125], v[186:189], 0
	v_mfma_f32_16x16x32_bf16 v[78:81], v[114:117], v[200:203], 0
	v_mfma_f32_16x16x32_bf16 v[74:77], v[122:125], v[200:203], 0
	v_mfma_f32_16x16x32_bf16 v[158:161], v[118:121], v[166:169], v[158:161]
	v_mfma_f32_16x16x32_bf16 v[150:153], v[126:129], v[166:169], v[150:153]
	v_mfma_f32_16x16x32_bf16 v[110:113], v[118:121], v[174:177], v[110:113]
	v_mfma_f32_16x16x32_bf16 v[106:109], v[126:129], v[174:177], v[106:109]
	v_mfma_f32_16x16x32_bf16 v[94:97], v[118:121], v[190:193], v[94:97]
	v_mfma_f32_16x16x32_bf16 v[90:93], v[126:129], v[190:193], v[90:93]
	v_mfma_f32_16x16x32_bf16 v[78:81], v[118:121], v[206:209], v[78:81]
	v_mfma_f32_16x16x32_bf16 v[74:77], v[126:129], v[206:209], v[74:77]
	v_mfma_f32_16x16x32_bf16 v[142:145], v[134:137], v[162:165], 0
	v_mfma_f32_16x16x32_bf16 v[130:133], v[146:149], v[162:165], 0
	v_mfma_f32_16x16x32_bf16 v[102:105], v[134:137], v[170:173], 0
	v_mfma_f32_16x16x32_bf16 v[98:101], v[146:149], v[170:173], 0
	v_mfma_f32_16x16x32_bf16 v[86:89], v[134:137], v[186:189], 0
	v_mfma_f32_16x16x32_bf16 v[82:85], v[146:149], v[186:189], 0
	v_mfma_f32_16x16x32_bf16 v[70:73], v[134:137], v[200:203], 0
	v_mfma_f32_16x16x32_bf16 v[66:69], v[146:149], v[200:203], 0
	v_mfma_f32_16x16x32_bf16 v[142:145], v[138:141], v[166:169], v[142:145]
	v_mfma_f32_16x16x32_bf16 v[130:133], v[154:157], v[166:169], v[130:133]
	v_mfma_f32_16x16x32_bf16 v[102:105], v[138:141], v[174:177], v[102:105]
	v_mfma_f32_16x16x32_bf16 v[98:101], v[154:157], v[174:177], v[98:101]
	v_mfma_f32_16x16x32_bf16 v[86:89], v[138:141], v[190:193], v[86:89]
	v_mfma_f32_16x16x32_bf16 v[82:85], v[154:157], v[190:193], v[82:85]
	v_mfma_f32_16x16x32_bf16 v[70:73], v[138:141], v[206:209], v[70:73]
	v_mfma_f32_16x16x32_bf16 v[66:69], v[154:157], v[206:209], v[66:69]
	s_barrier
	s_add_i32 s18, s18, s37
	v_lshl_add_u64 v[204:205], s[62:63], 0, v[178:179]
	s_mov_b32 m0, s18
	ds_read_b128 v[162:165], v217 offset:16384
	ds_read_b128 v[166:169], v217 offset:17408
	ds_read_b128 v[170:173], v217 offset:18432
	ds_read_b128 v[174:177], v217 offset:19456
	ds_read_b128 v[186:189], v217 offset:20480
	ds_read_b128 v[190:193], v217 offset:21504
	ds_read_b128 v[200:203], v217 offset:22528
	ds_read_b128 v[206:209], v217 offset:23552
	global_load_lds_dwordx4 v[204:205], off
	s_add_i32 m0, s18, 0x2000
	s_add_u32 s18, s62, 0xb0000
	v_lshl_add_u64 v[210:211], s[62:63], 0, v[180:181]
	s_addc_u32 s19, s63, 0
	s_add_i32 s58, s81, s37
	global_load_lds_dwordx4 v[210:211], off
	s_mov_b32 m0, s58
	v_lshl_add_u64 v[214:215], s[64:65], 0, v[180:181]
	global_load_lds_dwordx4 v178, s[18:19]
	s_add_i32 m0, s58, 0x2000
	s_nop 0
	global_load_lds_dwordx4 v180, s[18:19]
	v_lshl_add_u64 v[212:213], s[64:65], 0, v[178:179]
	s_mov_b32 m0, s66
	s_nop 0
	global_load_lds_dwordx4 v[212:213], off
	s_mov_b32 m0, s67
	s_nop 0
	global_load_lds_dwordx4 v[214:215], off
	s_waitcnt vmcnt(8)
	s_waitcnt lgkmcnt(0)
	s_barrier
	s_waitcnt lgkmcnt(0)
	v_mfma_f32_16x16x32_bf16 v[62:65], v[114:117], v[162:165], 0
	v_mfma_f32_16x16x32_bf16 v[58:61], v[122:125], v[162:165], 0
	v_mfma_f32_16x16x32_bf16 v[46:49], v[114:117], v[170:173], 0
	v_mfma_f32_16x16x32_bf16 v[42:45], v[122:125], v[170:173], 0
	v_mfma_f32_16x16x32_bf16 v[30:33], v[114:117], v[186:189], 0
	v_mfma_f32_16x16x32_bf16 v[26:29], v[122:125], v[186:189], 0
	v_mfma_f32_16x16x32_bf16 v[14:17], v[114:117], v[200:203], 0
	v_mfma_f32_16x16x32_bf16 v[10:13], v[122:125], v[200:203], 0
	v_mfma_f32_16x16x32_bf16 v[62:65], v[118:121], v[166:169], v[62:65]
	v_mfma_f32_16x16x32_bf16 v[58:61], v[126:129], v[166:169], v[58:61]
	v_mfma_f32_16x16x32_bf16 v[46:49], v[118:121], v[174:177], v[46:49]
	v_mfma_f32_16x16x32_bf16 v[42:45], v[126:129], v[174:177], v[42:45]
	v_mfma_f32_16x16x32_bf16 v[30:33], v[118:121], v[190:193], v[30:33]
	v_mfma_f32_16x16x32_bf16 v[26:29], v[126:129], v[190:193], v[26:29]
	v_mfma_f32_16x16x32_bf16 v[14:17], v[118:121], v[206:209], v[14:17]
	v_mfma_f32_16x16x32_bf16 v[10:13], v[126:129], v[206:209], v[10:13]
	v_mfma_f32_16x16x32_bf16 v[54:57], v[134:137], v[162:165], 0
	v_mfma_f32_16x16x32_bf16 v[50:53], v[146:149], v[162:165], 0
	v_mfma_f32_16x16x32_bf16 v[38:41], v[134:137], v[170:173], 0
	v_mfma_f32_16x16x32_bf16 v[34:37], v[146:149], v[170:173], 0
	v_mfma_f32_16x16x32_bf16 v[22:25], v[134:137], v[186:189], 0
	v_mfma_f32_16x16x32_bf16 v[18:21], v[146:149], v[186:189], 0
	v_mfma_f32_16x16x32_bf16 v[6:9], v[134:137], v[200:203], 0
	v_mfma_f32_16x16x32_bf16 v[2:5], v[146:149], v[200:203], 0
	v_mfma_f32_16x16x32_bf16 v[54:57], v[138:141], v[166:169], v[54:57]
	v_mfma_f32_16x16x32_bf16 v[50:53], v[154:157], v[166:169], v[50:53]
	v_mfma_f32_16x16x32_bf16 v[38:41], v[138:141], v[174:177], v[38:41]
	v_mfma_f32_16x16x32_bf16 v[34:37], v[154:157], v[174:177], v[34:37]
	v_mfma_f32_16x16x32_bf16 v[22:25], v[138:141], v[190:193], v[22:25]
	v_mfma_f32_16x16x32_bf16 v[18:21], v[154:157], v[190:193], v[18:21]
	v_mfma_f32_16x16x32_bf16 v[6:9], v[138:141], v[206:209], v[6:9]
	v_mfma_f32_16x16x32_bf16 v[2:5], v[154:157], v[206:209], v[2:5]
	s_barrier
	s_branch .Lp3_down
; #define PG8_STAGE(bufoff, gbase, voff) do { _Pragma("unroll") for (int _i = 0; _i < 2; ++_i) \
;         __builtin_amdgcn_global_load_lds((const unsigned*)((const char*)(gbase) + (voff)[_i]), (LAS unsigned*)(lds + (bufoff) + ldsw + _i * 8192), 16, 0, 0); } while (0)
; #define PG8_LDA(dst, b, h) do { _Pragma("unroll") for (int m = 0; m < 4; ++m) _Pragma("unroll") for (int k = 0; k < 2; ++k) dst[m][k] = *(const LAS bf16x8*)(lds + PG8_SA(b, h) + aoff + m * 2048 + k * 1024); } while (0)
; #define PG8_LDB(dst, b, h) do { _Pragma("unroll") for (int n = 0; n < 2; ++n) _Pragma("unroll") for (int k = 0; k < 2; ++k) dst[n][k] = *(const LAS bf16x8*)(lds + PG8_SB(b, h) + boff + n * 2048 + k * 1024); } while (0)
; #define PG8_MMA(ai, bj, At, Bt) do { __builtin_amdgcn_s_setprio(1); _Pragma("unroll") for (int m = 0; m < 4; ++m) _Pragma("unroll") for (int n = 0; n < 2; ++n) _Pragma("unroll") for (int k = 0; k < 2; ++k) \
;         acc[ai][bj][m][n] = __builtin_amdgcn_mfma_f32_16x16x32_bf16(Bt[n][k], At[m][k], acc[ai][bj][m][n], 0, 0, 0); __builtin_amdgcn_s_setprio(0); } while (0)
; #define PG8_WAIT_V(n) asm volatile("s_waitcnt vmcnt(" #n ")" ::: "memory")
; #define PG8_WAIT_L(n) asm volatile("s_waitcnt lgkmcnt(" #n ")" ::: "memory")
; #define PG8_BAR __builtin_amdgcn_s_barrier()
; #define PG8_SCHED __builtin_amdgcn_sched_barrier(0)
; template <class Epi>
; DI void gemm_phase(LAS unsigned char* lds, const Gemm g, const StaticOrder& S, const Epi& E) {
;     ...
;             PG8_LDB(B0, 0, 0); PG8_LDB(B1, 0, 1); PG8_SCHED; PG8_LDA(At, 0, 0); PG8_STAGE(PG8_SA(1, 1), a1 + hstep, voffA);
;             PG8_WAIT_V(8); PG8_WAIT_L(0); PG8_BAR; PG8_MMA(0, 0, At, B0); PG8_MMA(0, 1, At, B1); PG8_BAR; PG8_SCHED;
;             PG8_LDA(At, 0, 1); PG8_STAGE(PG8_SB(0, 0), b2, voffB); PG8_STAGE(PG8_SB(0, 1), b2 + hstep, voffB); PG8_STAGE(PG8_SA(0, 0), a2, voffA);
;             PG8_WAIT_V(8); PG8_WAIT_L(0); PG8_BAR; PG8_MMA(1, 0, At, B0); PG8_MMA(1, 1, At, B1); PG8_BAR; PG8_SCHED;
.LBB0_783:
	s_add_u32 s60, s58, 0x100
	s_addc_u32 s61, s59, 0
	s_add_i32 s18, 0, 0x10000
	s_cmp_eq_u32 s93, 40
	s_cselect_b32 s65, s9, s61
	s_cselect_b32 s64, s8, s60
	s_cselect_b32 s63, s57, s91
	s_cselect_b32 s62, s56, s73
	s_add_i32 s81, 0, 0x14000
	v_add_u32_e32 v126, s18, v195
	v_add_u32_e32 v154, s81, v195
	ds_read_b128 v[114:117], v126
	ds_read_b128 v[118:121], v126 offset:1024
	ds_read_b128 v[122:125], v126 offset:2048
	ds_read_b128 v[126:129], v126 offset:3072
	ds_read_b128 v[134:137], v154
	ds_read_b128 v[138:141], v154 offset:1024
	ds_read_b128 v[146:149], v154 offset:2048
	ds_read_b128 v[154:157], v154 offset:3072
	v_lshl_add_u64 v[204:205], s[58:59], 0, v[184:185]
	s_add_i32 m0, s66, 0xc000
	ds_read_b128 v[162:165], v217
	ds_read_b128 v[166:169], v217 offset:1024
	ds_read_b128 v[170:173], v217 offset:2048
	ds_read_b128 v[174:177], v217 offset:3072
	ds_read_b128 v[186:189], v217 offset:4096
	ds_read_b128 v[190:193], v217 offset:5120
	ds_read_b128 v[200:203], v217 offset:6144
	ds_read_b128 v[206:209], v217 offset:7168
	global_load_lds_dwordx4 v[204:205], off
	v_lshl_add_u64 v[204:205], s[58:59], 0, v[182:183]
	s_add_i32 m0, s66, 0xe000
	s_nop 0
	global_load_lds_dwordx4 v[204:205], off
	s_waitcnt vmcnt(8)
	s_waitcnt lgkmcnt(0)
	s_barrier
	s_waitcnt lgkmcnt(0)
	v_mfma_f32_16x16x32_bf16 v[158:161], v[114:117], v[162:165], v[158:161]
	v_mfma_f32_16x16x32_bf16 v[150:153], v[122:125], v[162:165], v[150:153]
	v_mfma_f32_16x16x32_bf16 v[110:113], v[114:117], v[170:173], v[110:113]
	v_mfma_f32_16x16x32_bf16 v[106:109], v[122:125], v[170:173], v[106:109]
	v_mfma_f32_16x16x32_bf16 v[94:97], v[114:117], v[186:189], v[94:97]
	v_mfma_f32_16x16x32_bf16 v[90:93], v[122:125], v[186:189], v[90:93]
	v_mfma_f32_16x16x32_bf16 v[78:81], v[114:117], v[200:203], v[78:81]
	v_mfma_f32_16x16x32_bf16 v[74:77], v[122:125], v[200:203], v[74:77]
	v_mfma_f32_16x16x32_bf16 v[158:161], v[118:121], v[166:169], v[158:161]
	v_mfma_f32_16x16x32_bf16 v[150:153], v[126:129], v[166:169], v[150:153]
	v_mfma_f32_16x16x32_bf16 v[110:113], v[118:121], v[174:177], v[110:113]
	v_mfma_f32_16x16x32_bf16 v[106:109], v[126:129], v[174:177], v[106:109]
	v_mfma_f32_16x16x32_bf16 v[94:97], v[118:121], v[190:193], v[94:97]
	v_mfma_f32_16x16x32_bf16 v[90:93], v[126:129], v[190:193], v[90:93]
	v_mfma_f32_16x16x32_bf16 v[78:81], v[118:121], v[206:209], v[78:81]
	v_mfma_f32_16x16x32_bf16 v[74:77], v[126:129], v[206:209], v[74:77]
	v_mfma_f32_16x16x32_bf16 v[142:145], v[134:137], v[162:165], v[142:145]
	v_mfma_f32_16x16x32_bf16 v[130:133], v[146:149], v[162:165], v[130:133]
	v_mfma_f32_16x16x32_bf16 v[102:105], v[134:137], v[170:173], v[102:105]
	v_mfma_f32_16x16x32_bf16 v[98:101], v[146:149], v[170:173], v[98:101]
	v_mfma_f32_16x16x32_bf16 v[86:89], v[134:137], v[186:189], v[86:89]
	v_mfma_f32_16x16x32_bf16 v[82:85], v[146:149], v[186:189], v[82:85]
	v_mfma_f32_16x16x32_bf16 v[70:73], v[134:137], v[200:203], v[70:73]
	v_mfma_f32_16x16x32_bf16 v[66:69], v[146:149], v[200:203], v[66:69]
	v_mfma_f32_16x16x32_bf16 v[142:145], v[138:141], v[166:169], v[142:145]
	v_mfma_f32_16x16x32_bf16 v[130:133], v[154:157], v[166:169], v[130:133]
	v_mfma_f32_16x16x32_bf16 v[102:105], v[138:141], v[174:177], v[102:105]
	v_mfma_f32_16x16x32_bf16 v[98:101], v[154:157], v[174:177], v[98:101]
	v_mfma_f32_16x16x32_bf16 v[86:89], v[138:141], v[190:193], v[86:89]
	v_mfma_f32_16x16x32_bf16 v[82:85], v[154:157], v[190:193], v[82:85]
	v_mfma_f32_16x16x32_bf16 v[70:73], v[138:141], v[206:209], v[70:73]
	v_mfma_f32_16x16x32_bf16 v[66:69], v[154:157], v[206:209], v[66:69]
	s_barrier
	s_add_i32 s18, s18, s37
	v_lshl_add_u64 v[204:205], s[62:63], 0, v[178:179]
	s_mov_b32 m0, s18
	ds_read_b128 v[162:165], v217 offset:16384
	ds_read_b128 v[166:169], v217 offset:17408
	ds_read_b128 v[170:173], v217 offset:18432
	ds_read_b128 v[174:177], v217 offset:19456
	ds_read_b128 v[186:189], v217 offset:20480
	ds_read_b128 v[190:193], v217 offset:21504
	ds_read_b128 v[200:203], v217 offset:22528
	ds_read_b128 v[206:209], v217 offset:23552
	global_load_lds_dwordx4 v[204:205], off
	s_add_i32 m0, s18, 0x2000
	s_add_u32 s18, s62, 0xb0000
	v_lshl_add_u64 v[210:211], s[62:63], 0, v[180:181]
	s_addc_u32 s19, s63, 0
	s_add_i32 s58, s81, s37
	global_load_lds_dwordx4 v[210:211], off
	s_mov_b32 m0, s58
	v_lshl_add_u64 v[214:215], s[64:65], 0, v[180:181]
	global_load_lds_dwordx4 v178, s[18:19]
	s_add_i32 m0, s58, 0x2000
	s_nop 0
	global_load_lds_dwordx4 v180, s[18:19]
	v_lshl_add_u64 v[212:213], s[64:65], 0, v[178:179]
	s_mov_b32 m0, s66
	s_nop 0
	global_load_lds_dwordx4 v[212:213], off
	s_mov_b32 m0, s67
	s_nop 0
	global_load_lds_dwordx4 v[214:215], off
	s_waitcnt vmcnt(8)
	s_waitcnt lgkmcnt(0)
	s_barrier
	s_waitcnt lgkmcnt(0)
	v_mfma_f32_16x16x32_bf16 v[62:65], v[114:117], v[162:165], v[62:65]
	v_mfma_f32_16x16x32_bf16 v[58:61], v[122:125], v[162:165], v[58:61]
	v_mfma_f32_16x16x32_bf16 v[46:49], v[114:117], v[170:173], v[46:49]
	v_mfma_f32_16x16x32_bf16 v[42:45], v[122:125], v[170:173], v[42:45]
	v_mfma_f32_16x16x32_bf16 v[30:33], v[114:117], v[186:189], v[30:33]
	v_mfma_f32_16x16x32_bf16 v[26:29], v[122:125], v[186:189], v[26:29]
	v_mfma_f32_16x16x32_bf16 v[14:17], v[114:117], v[200:203], v[14:17]
	v_mfma_f32_16x16x32_bf16 v[10:13], v[122:125], v[200:203], v[10:13]
	v_mfma_f32_16x16x32_bf16 v[62:65], v[118:121], v[166:169], v[62:65]
	v_mfma_f32_16x16x32_bf16 v[58:61], v[126:129], v[166:169], v[58:61]
	v_mfma_f32_16x16x32_bf16 v[46:49], v[118:121], v[174:177], v[46:49]
	v_mfma_f32_16x16x32_bf16 v[42:45], v[126:129], v[174:177], v[42:45]
	v_mfma_f32_16x16x32_bf16 v[30:33], v[118:121], v[190:193], v[30:33]
	v_mfma_f32_16x16x32_bf16 v[26:29], v[126:129], v[190:193], v[26:29]
	v_mfma_f32_16x16x32_bf16 v[14:17], v[118:121], v[206:209], v[14:17]
	v_mfma_f32_16x16x32_bf16 v[10:13], v[126:129], v[206:209], v[10:13]
	v_mfma_f32_16x16x32_bf16 v[54:57], v[134:137], v[162:165], v[54:57]
	v_mfma_f32_16x16x32_bf16 v[50:53], v[146:149], v[162:165], v[50:53]
	v_mfma_f32_16x16x32_bf16 v[38:41], v[134:137], v[170:173], v[38:41]
	v_mfma_f32_16x16x32_bf16 v[34:37], v[146:149], v[170:173], v[34:37]
	v_mfma_f32_16x16x32_bf16 v[22:25], v[134:137], v[186:189], v[22:25]
	v_mfma_f32_16x16x32_bf16 v[18:21], v[146:149], v[186:189], v[18:21]
	v_mfma_f32_16x16x32_bf16 v[6:9], v[134:137], v[200:203], v[6:9]
	v_mfma_f32_16x16x32_bf16 v[2:5], v[146:149], v[200:203], v[2:5]
	v_mfma_f32_16x16x32_bf16 v[54:57], v[138:141], v[166:169], v[54:57]
	v_mfma_f32_16x16x32_bf16 v[50:53], v[154:157], v[166:169], v[50:53]
	v_mfma_f32_16x16x32_bf16 v[38:41], v[138:141], v[174:177], v[38:41]
	v_mfma_f32_16x16x32_bf16 v[34:37], v[154:157], v[174:177], v[34:37]
	v_mfma_f32_16x16x32_bf16 v[22:25], v[138:141], v[190:193], v[22:25]
	v_mfma_f32_16x16x32_bf16 v[18:21], v[154:157], v[190:193], v[18:21]
	v_mfma_f32_16x16x32_bf16 v[6:9], v[138:141], v[206:209], v[6:9]
	v_mfma_f32_16x16x32_bf16 v[2:5], v[154:157], v[206:209], v[2:5]
	s_barrier
; #define PG8_STAGE(bufoff, gbase, voff) do { _Pragma("unroll") for (int _i = 0; _i < 2; ++_i) \
;         __builtin_amdgcn_global_load_lds((const unsigned*)((const char*)(gbase) + (voff)[_i]), (LAS unsigned*)(lds + (bufoff) + ldsw + _i * 8192), 16, 0, 0); } while (0)
; #define PG8_LDA(dst, b, h) do { _Pragma("unroll") for (int m = 0; m < 4; ++m) _Pragma("unroll") for (int k = 0; k < 2; ++k) dst[m][k] = *(const LAS bf16x8*)(lds + PG8_SA(b, h) + aoff + m * 2048 + k * 1024); } while (0)
; #define PG8_LDB(dst, b, h) do { _Pragma("unroll") for (int n = 0; n < 2; ++n) _Pragma("unroll") for (int k = 0; k < 2; ++k) dst[n][k] = *(const LAS bf16x8*)(lds + PG8_SB(b, h) + boff + n * 2048 + k * 1024); } while (0)
; #define PG8_MMA(ai, bj, At, Bt) do { __builtin_amdgcn_s_setprio(1); _Pragma("unroll") for (int m = 0; m < 4; ++m) _Pragma("unroll") for (int n = 0; n < 2; ++n) _Pragma("unroll") for (int k = 0; k < 2; ++k) \
;         acc[ai][bj][m][n] = __builtin_amdgcn_mfma_f32_16x16x32_bf16(Bt[n][k], At[m][k], acc[ai][bj][m][n], 0, 0, 0); __builtin_amdgcn_s_setprio(0); } while (0)
; #define PG8_WAIT_V(n) asm volatile("s_waitcnt vmcnt(" #n ")" ::: "memory")
; #define PG8_WAIT_L(n) asm volatile("s_waitcnt lgkmcnt(" #n ")" ::: "memory")
; #define PG8_BAR __builtin_amdgcn_s_barrier()
; #define PG8_SCHED __builtin_amdgcn_sched_barrier(0)
; template <class Epi>
; DI void gemm_phase(LAS unsigned char* lds, const Gemm g, const StaticOrder& S, const Epi& E) {
;     ...
;             PG8_LDB(B0, 1, 0); PG8_LDB(B1, 1, 1); PG8_SCHED; PG8_LDA(At, 1, 0); PG8_STAGE(PG8_SA(0, 1), a2 + hstep, voffA);
;             PG8_WAIT_V(8); PG8_WAIT_L(0); PG8_BAR; PG8_MMA(0, 0, At, B0); PG8_MMA(0, 1, At, B1); PG8_BAR; PG8_SCHED;
;             PG8_LDA(At, 1, 1); PG8_STAGE(PG8_SB(1, 0), b3, voffB); PG8_STAGE(PG8_SB(1, 1), b3 + hstep, voffB); PG8_STAGE(PG8_SA(1, 0), a3, voffA);
;             PG8_WAIT_V(8); PG8_WAIT_L(0); PG8_BAR; PG8_MMA(1, 0, At, B0); PG8_MMA(1, 1, At, B1); PG8_BAR; PG8_SCHED;
;         }
;         if (wr == 0) PG8_BAR;
.Lp3_down:
	s_add_i32 s58, 0, 0x18000
	s_add_i32 s59, 0, 0x1c000
	v_add_u32_e32 v126, s58, v195
	v_add_u32_e32 v154, s59, v195
	ds_read_b128 v[114:117], v126
	ds_read_b128 v[118:121], v126 offset:1024
	ds_read_b128 v[122:125], v126 offset:2048
	ds_read_b128 v[126:129], v126 offset:3072
	ds_read_b128 v[134:137], v154
	ds_read_b128 v[138:141], v154 offset:1024
	ds_read_b128 v[146:149], v154 offset:2048
	ds_read_b128 v[154:157], v154 offset:3072
	s_add_u32 s18, s64, 0xb0000
	s_addc_u32 s19, s65, 0
	s_mov_b32 m0, s68
	ds_read_b128 v[162:165], v217 offset:32768
	ds_read_b128 v[166:169], v217 offset:33792
	ds_read_b128 v[170:173], v217 offset:34816
	ds_read_b128 v[174:177], v217 offset:35840
	ds_read_b128 v[186:189], v217 offset:36864
	ds_read_b128 v[190:193], v217 offset:37888
	ds_read_b128 v[200:203], v217 offset:38912
	ds_read_b128 v[206:209], v217 offset:39936
	global_load_lds_dwordx4 v178, s[18:19]
	v_lshl_add_u64 v[218:219], s[18:19], 0, v[180:181]
	s_mov_b32 m0, s69
	s_nop 0
	global_load_lds_dwordx4 v[218:219], off
	s_waitcnt vmcnt(8)
	s_waitcnt lgkmcnt(0)
	s_barrier
	s_waitcnt lgkmcnt(0)
	v_mfma_f32_16x16x32_bf16 v[158:161], v[114:117], v[162:165], v[158:161]
	v_mfma_f32_16x16x32_bf16 v[150:153], v[122:125], v[162:165], v[150:153]
	v_mfma_f32_16x16x32_bf16 v[110:113], v[114:117], v[170:173], v[110:113]
	v_mfma_f32_16x16x32_bf16 v[106:109], v[122:125], v[170:173], v[106:109]
	v_mfma_f32_16x16x32_bf16 v[94:97], v[114:117], v[186:189], v[94:97]
	v_mfma_f32_16x16x32_bf16 v[90:93], v[122:125], v[186:189], v[90:93]
	v_mfma_f32_16x16x32_bf16 v[78:81], v[114:117], v[200:203], v[78:81]
	v_mfma_f32_16x16x32_bf16 v[74:77], v[122:125], v[200:203], v[74:77]
	v_mfma_f32_16x16x32_bf16 v[158:161], v[118:121], v[166:169], v[158:161]
	v_mfma_f32_16x16x32_bf16 v[150:153], v[126:129], v[166:169], v[150:153]
	v_mfma_f32_16x16x32_bf16 v[110:113], v[118:121], v[174:177], v[110:113]
	v_mfma_f32_16x16x32_bf16 v[106:109], v[126:129], v[174:177], v[106:109]
	v_mfma_f32_16x16x32_bf16 v[94:97], v[118:121], v[190:193], v[94:97]
	v_mfma_f32_16x16x32_bf16 v[90:93], v[126:129], v[190:193], v[90:93]
	v_mfma_f32_16x16x32_bf16 v[78:81], v[118:121], v[206:209], v[78:81]
	v_mfma_f32_16x16x32_bf16 v[74:77], v[126:129], v[206:209], v[74:77]
	v_mfma_f32_16x16x32_bf16 v[142:145], v[134:137], v[162:165], v[142:145]
	v_mfma_f32_16x16x32_bf16 v[130:133], v[146:149], v[162:165], v[130:133]
	v_mfma_f32_16x16x32_bf16 v[102:105], v[134:137], v[170:173], v[102:105]
	v_mfma_f32_16x16x32_bf16 v[98:101], v[146:149], v[170:173], v[98:101]
	v_mfma_f32_16x16x32_bf16 v[86:89], v[134:137], v[186:189], v[86:89]
	v_mfma_f32_16x16x32_bf16 v[82:85], v[146:149], v[186:189], v[82:85]
	v_mfma_f32_16x16x32_bf16 v[70:73], v[134:137], v[200:203], v[70:73]
	v_mfma_f32_16x16x32_bf16 v[66:69], v[146:149], v[200:203], v[66:69]
	v_mfma_f32_16x16x32_bf16 v[142:145], v[138:141], v[166:169], v[142:145]
	v_mfma_f32_16x16x32_bf16 v[130:133], v[154:157], v[166:169], v[130:133]
	v_mfma_f32_16x16x32_bf16 v[102:105], v[138:141], v[174:177], v[102:105]
	v_mfma_f32_16x16x32_bf16 v[98:101], v[154:157], v[174:177], v[98:101]
	v_mfma_f32_16x16x32_bf16 v[86:89], v[138:141], v[190:193], v[86:89]
	v_mfma_f32_16x16x32_bf16 v[82:85], v[154:157], v[190:193], v[82:85]
	v_mfma_f32_16x16x32_bf16 v[70:73], v[138:141], v[206:209], v[70:73]
	v_mfma_f32_16x16x32_bf16 v[66:69], v[154:157], v[206:209], v[66:69]
	s_barrier
	s_add_i32 s18, s58, s37
	v_lshl_add_u64 v[204:205], v[204:205], 0, s[20:21]
	s_mov_b32 m0, s18
	ds_read_b128 v[162:165], v217 offset:49152
	ds_read_b128 v[166:169], v217 offset:50176
	ds_read_b128 v[170:173], v217 offset:51200
	ds_read_b128 v[174:177], v217 offset:52224
	ds_read_b128 v[186:189], v217 offset:53248
	ds_read_b128 v[190:193], v217 offset:54272
	ds_read_b128 v[200:203], v217 offset:55296
	ds_read_b128 v[206:209], v217 offset:56320
	global_load_lds_dwordx4 v[204:205], off
	s_add_i32 m0, s18, 0x2000
	s_add_u32 s18, s62, 0xb0080
	v_lshl_add_u64 v[204:205], v[210:211], 0, s[20:21]
	s_addc_u32 s19, s63, 0
	s_add_i32 s58, s59, s37
	global_load_lds_dwordx4 v[204:205], off
	s_mov_b32 m0, s58
	s_nop 0
	global_load_lds_dwordx4 v178, s[18:19]
	s_add_i32 m0, s58, 0x2000
	s_nop 0
	global_load_lds_dwordx4 v180, s[18:19]
	v_lshl_add_u64 v[204:205], v[212:213], 0, s[20:21]
	s_mov_b32 m0, s71
	s_nop 0
	global_load_lds_dwordx4 v[204:205], off
	v_lshl_add_u64 v[204:205], v[214:215], 0, s[20:21]
	s_mov_b32 m0, s17
	s_nop 0
	global_load_lds_dwordx4 v[204:205], off
	s_waitcnt vmcnt(8)
	s_waitcnt lgkmcnt(0)
	s_barrier
	s_waitcnt lgkmcnt(0)
	v_mfma_f32_16x16x32_bf16 v[62:65], v[114:117], v[162:165], v[62:65]
	v_mfma_f32_16x16x32_bf16 v[58:61], v[122:125], v[162:165], v[58:61]
	v_mfma_f32_16x16x32_bf16 v[46:49], v[114:117], v[170:173], v[46:49]
	v_mfma_f32_16x16x32_bf16 v[42:45], v[122:125], v[170:173], v[42:45]
	v_mfma_f32_16x16x32_bf16 v[30:33], v[114:117], v[186:189], v[30:33]
	v_mfma_f32_16x16x32_bf16 v[26:29], v[122:125], v[186:189], v[26:29]
	v_mfma_f32_16x16x32_bf16 v[14:17], v[114:117], v[200:203], v[14:17]
	v_mfma_f32_16x16x32_bf16 v[10:13], v[122:125], v[200:203], v[10:13]
	v_mfma_f32_16x16x32_bf16 v[62:65], v[118:121], v[166:169], v[62:65]
	v_mfma_f32_16x16x32_bf16 v[58:61], v[126:129], v[166:169], v[58:61]
	v_mfma_f32_16x16x32_bf16 v[46:49], v[118:121], v[174:177], v[46:49]
	v_mfma_f32_16x16x32_bf16 v[42:45], v[126:129], v[174:177], v[42:45]
	v_mfma_f32_16x16x32_bf16 v[30:33], v[118:121], v[190:193], v[30:33]
	v_mfma_f32_16x16x32_bf16 v[26:29], v[126:129], v[190:193], v[26:29]
	v_mfma_f32_16x16x32_bf16 v[14:17], v[118:121], v[206:209], v[14:17]
	v_mfma_f32_16x16x32_bf16 v[10:13], v[126:129], v[206:209], v[10:13]
	v_mfma_f32_16x16x32_bf16 v[54:57], v[134:137], v[162:165], v[54:57]
	v_mfma_f32_16x16x32_bf16 v[50:53], v[146:149], v[162:165], v[50:53]
	v_mfma_f32_16x16x32_bf16 v[38:41], v[134:137], v[170:173], v[38:41]
	v_mfma_f32_16x16x32_bf16 v[34:37], v[146:149], v[170:173], v[34:37]
	v_mfma_f32_16x16x32_bf16 v[22:25], v[134:137], v[186:189], v[22:25]
	v_mfma_f32_16x16x32_bf16 v[18:21], v[146:149], v[186:189], v[18:21]
	v_mfma_f32_16x16x32_bf16 v[6:9], v[134:137], v[200:203], v[6:9]
	v_mfma_f32_16x16x32_bf16 v[2:5], v[146:149], v[200:203], v[2:5]
	v_mfma_f32_16x16x32_bf16 v[54:57], v[138:141], v[166:169], v[54:57]
	v_mfma_f32_16x16x32_bf16 v[50:53], v[154:157], v[166:169], v[50:53]
	v_mfma_f32_16x16x32_bf16 v[38:41], v[138:141], v[174:177], v[38:41]
	v_mfma_f32_16x16x32_bf16 v[34:37], v[154:157], v[174:177], v[34:37]
	v_mfma_f32_16x16x32_bf16 v[22:25], v[138:141], v[190:193], v[22:25]
	v_mfma_f32_16x16x32_bf16 v[18:21], v[154:157], v[190:193], v[18:21]
	v_mfma_f32_16x16x32_bf16 v[6:9], v[138:141], v[206:209], v[6:9]
	v_mfma_f32_16x16x32_bf16 v[2:5], v[154:157], v[206:209], v[2:5]
	s_barrier
	s_add_i32 s93, s93, 2
	s_add_u32 s73, s73, 0x100
	s_addc_u32 s91, s91, 0
	s_cmp_gt_u32 s93, 41
	s_mov_b64 s[58:59], s[60:61]
	s_cbranch_scc0 .LBB0_783
	s_setprio 0
	s_and_b64 vcc, exec, s[54:55]
	s_cbranch_vccz .LBB0_786
	s_barrier
